# samplebegin on v111: P5 sample-tile item start issues all 22 loads back to back (address temporaries renamed) instead of waiting for the first five before the fragment loads
# baseline (speedup 1.0000x reference)
.LBB0_1023:
	s_ashr_i32 s9, s8, 31
	s_mul_i32 s7, s8, 0x88000
	s_mul_hi_i32 s6, s8, 0x88000
	s_add_u32 s7, s4, s7
	s_addc_u32 s10, s5, s6
	s_add_u32 s6, s7, 0x80000
	s_addc_u32 s7, s10, 0
	v_lshl_add_u64 v[128:129], s[6:7], 0, v[122:123]
	s_movk_i32 s10, 0x2000
	global_load_dwordx4 v[38:41], v122, s[6:7]
	global_load_dwordx4 v[46:49], v124, s[6:7]
	v_add_co_u32_e32 v2, vcc, s10, v128
	v_lshl_add_u64 v[132:133], s[6:7], 0, v[124:125]
	s_mov_b64 s[6:7], 0x6000
	v_addc_co_u32_e32 v3, vcc, 0, v129, vcc
	v_lshl_add_u64 v[134:135], v[128:129], 0, s[6:7]
	s_movk_i32 s6, 0x6000
	global_load_dwordx4 v[42:45], v[2:3], off
	v_add_co_u32_e32 v2, vcc, s6, v128
	s_lshl_b64 s[6:7], s[8:9], 14
	v_lshl_add_u64 v[10:11], v[116:117], 0, s[6:7]
	v_addc_co_u32_e32 v3, vcc, 0, v129, vcc
	v_lshl_add_u64 v[6:7], v[10:11], 0, v[126:127]
	global_load_dwordx4 v[50:53], v[2:3], off
	s_nop 0
	global_load_dwordx4 v[2:5], v[6:7], off
	s_nop 0
	global_load_dwordx4 v[6:9], v[6:7], off offset:16
	v_readfirstlane_b32 s46, v0
	s_lshr_b32 s10, s46, 6
	s_lshl_b64 s[28:29], s[8:9], 16
	s_lshl_b64 s[6:7], s[10:11], 10
	s_mov_b64 s[14:15], 0x2000
	v_lshl_add_u64 v[130:131], v[128:129], 0, s[14:15]
	s_add_i32 s14, s10, 8
	s_mov_b32 s15, s11
	s_lshl_b64 s[14:15], s[14:15], 10
	s_sub_i32 s26, 15, s10
	s_ashr_i32 s27, s26, 31
	v_lshl_or_b32 v90, s8, 6, v186
	v_ashrrev_i32_e32 v91, 31, v90
	v_lshl_add_u64 v[90:91], v[90:91], 3, s[12:13]
	v_readlane_b32 s72, v254, 10
	v_readlane_b32 s78, v254, 16
	v_readlane_b32 s79, v254, 17
	v_readlane_b32 s80, v254, 18
	v_readlane_b32 s81, v254, 19
	s_mov_b64 s[58:59], s[78:79]
	v_readlane_b32 s82, v254, 20
	v_readlane_b32 s83, v254, 21
	v_readlane_b32 s84, v254, 22
	v_readlane_b32 s85, v254, 23
	v_readlane_b32 s86, v254, 24
	v_readlane_b32 s87, v254, 25
	s_mov_b64 s[60:61], s[80:81]
	s_mov_b32 s45, 0
	v_lshl_add_u32 v155, s10, 10, v143
	v_readlane_b32 s73, v254, 11
	v_readlane_b32 s74, v254, 12
	v_readlane_b32 s75, v254, 13
	v_readlane_b32 s76, v254, 14
	v_readlane_b32 s77, v254, 15
	s_mov_b64 s[62:63], s[82:83]
	s_mov_b64 s[64:65], s[84:85]
	s_mov_b64 s[66:67], s[86:87]
	v_lshl_add_u64 v[236:237], v[114:115], 2, v[10:11]
	global_load_dwordx4 v[66:69], v[236:237], off offset:16
	global_load_dwordx4 v[70:73], v[236:237], off
	v_lshl_add_u64 v[236:237], v[118:119], 0, s[28:29]
	v_lshl_add_u64 v[238:239], v[236:237], 0, s[6:7]
	global_load_dwordx4 v[34:37], v[238:239], off
	v_lshl_add_u64 v[238:239], v[236:237], 0, s[14:15]
	global_load_dwordx4 v[54:57], v[238:239], off
	s_add_i32 s14, s10, 16
	s_mov_b32 s15, s11
	s_lshl_b64 s[30:31], s[14:15], 10
	v_lshl_add_u64 v[238:239], v[236:237], 0, s[30:31]
	global_load_dwordx4 v[58:61], v[238:239], off
	s_add_i32 s14, s10, 24
	s_lshl_b64 s[14:15], s[14:15], 10
	v_lshl_add_u64 v[238:239], v[236:237], 0, s[14:15]
	global_load_dwordx4 v[62:65], v[238:239], off
	s_add_i32 s14, s10, 32
	s_mov_b32 s15, s11
	s_lshl_b64 s[34:35], s[14:15], 10
	v_lshl_add_u64 v[238:239], v[236:237], 0, s[34:35]
	global_load_dwordx4 v[74:77], v[238:239], off
	s_add_i32 s14, s10, 40
	s_lshl_b64 s[14:15], s[14:15], 10
	v_lshl_add_u64 v[238:239], v[236:237], 0, s[14:15]
	global_load_dwordx4 v[78:81], v[238:239], off
	s_add_i32 s14, s10, 48
	s_mov_b32 s15, s11
	s_lshl_b64 s[38:39], s[14:15], 10
	v_lshl_add_u64 v[238:239], v[236:237], 0, s[38:39]
	global_load_dwordx4 v[82:85], v[238:239], off
	s_add_i32 s14, s10, 56
	s_lshl_b64 s[14:15], s[14:15], 10
	v_lshl_add_u64 v[236:237], v[236:237], 0, s[14:15]
	global_load_dwordx4 v[86:89], v[236:237], off
	v_lshl_add_u64 v[236:237], v[120:121], 0, s[28:29]
	v_lshl_add_u64 v[238:239], v[236:237], 0, s[6:7]
	global_load_dwordx4 v[30:33], v[238:239], off
	v_lshl_add_u64 v[238:239], v[236:237], 0, s[30:31]
	global_load_dwordx4 v[22:25], v[238:239], off
	v_lshl_add_u64 v[238:239], v[236:237], 0, s[34:35]
	global_load_dwordx4 v[26:29], v[238:239], off
	v_lshl_add_u64 v[238:239], v[236:237], 0, s[38:39]
	s_lshl_b64 s[6:7], s[26:27], 10
	global_load_dwordx4 v[18:21], v[238:239], off
	v_lshl_add_u64 v[238:239], v[236:237], 0, s[6:7]
	s_sub_i32 s6, 31, s10
	s_ashr_i32 s7, s6, 31
	s_lshl_b64 s[6:7], s[6:7], 10
	global_load_dwordx4 v[14:17], v[238:239], off
	v_lshl_add_u64 v[238:239], v[236:237], 0, s[6:7]
	s_sub_i32 s6, 47, s10
	s_ashr_i32 s7, s6, 31
	s_lshl_b64 s[6:7], s[6:7], 10
	global_load_dwordx4 v[10:13], v[238:239], off
	v_lshl_add_u64 v[238:239], v[236:237], 0, s[6:7]
	s_sub_i32 s6, 63, s10
	s_ashr_i32 s7, s6, 31
	s_lshl_b64 s[6:7], s[6:7], 10
	v_lshl_add_u64 v[236:237], v[236:237], 0, s[6:7]
	s_waitcnt vmcnt(16)
	v_cndmask_b32_e64 v98, v2, 0, s[0:1]
	v_cndmask_b32_e64 v99, v3, 0, s[0:1]
	v_cndmask_b32_e64 v96, v4, 0, s[0:1]
	v_cndmask_b32_e64 v97, v5, 0, s[0:1]
	v_cndmask_b32_e64 v92, v8, 0, s[0:1]
	v_cndmask_b32_e64 v93, v9, 0, s[0:1]
	v_cndmask_b32_e64 v94, v6, 0, s[0:1]
	v_cndmask_b32_e64 v95, v7, 0, s[0:1]
	global_load_dwordx4 v[6:9], v[238:239], off
	s_and_b32 s27, s46, 0xffffffc0
	global_load_dwordx4 v[2:5], v[236:237], off
	s_lshl_b32 s6, s10, 2
	global_load_dwordx2 v[90:91], v[90:91], off
	ds_write_b128 v148, v[38:41]
	ds_write_b128 v149, v[42:45]
	ds_write_b128 v150, v[46:49]
	ds_write_b128 v151, v[50:53]
	v_cvt_pk_bf16_f32 v38, v98, v99
	v_cvt_pk_bf16_f32 v39, v96, v97
	v_cvt_pk_bf16_f32 v40, v94, v95
	v_cvt_pk_bf16_f32 v41, v92, v93
	ds_write_b128 v153, v[38:41]
	s_waitcnt vmcnt(17)
	v_cvt_pk_bf16_f32 v38, v70, v71
	v_cvt_pk_bf16_f32 v39, v72, v73
	v_cvt_pk_bf16_f32 v40, v66, v67
	v_cvt_pk_bf16_f32 v41, v68, v69
	ds_write_b128 v153, v[38:41] offset:8192
	s_waitcnt lgkmcnt(0)
	s_waitcnt lgkmcnt(0)
	s_barrier
	ds_read_b128 v[38:41], v154
	ds_read_b128 v[42:45], v154 offset:64
	s_waitcnt vmcnt(16) lgkmcnt(1)
	v_mfma_f32_16x16x32_bf16 v[38:41], v[34:37], v[38:41], 0
	v_add3_u32 v46, v141, s27, v142
	s_lshl_b64 s[14:15], s[8:9], 6
	s_mov_b32 s7, s11
	s_waitcnt vmcnt(15) lgkmcnt(0)
	v_mfma_f32_16x16x32_bf16 v[38:41], v[54:57], v[42:45], v[38:41]
	ds_read_b128 v[42:45], v154 offset:128
	s_mul_i32 s9, s10, 0x880
	s_or_b32 s28, s6, 1
	s_waitcnt vmcnt(14) lgkmcnt(0)
	v_mfma_f32_16x16x32_bf16 v[38:41], v[58:61], v[42:45], v[38:41]
	ds_read_b128 v[42:45], v154 offset:192
	s_mov_b32 s29, s11
	s_waitcnt vmcnt(13) lgkmcnt(0)
	v_mfma_f32_16x16x32_bf16 v[38:41], v[62:65], v[42:45], v[38:41]
	ds_read_b128 v[42:45], v154 offset:256
	s_waitcnt vmcnt(12) lgkmcnt(0)
	v_mfma_f32_16x16x32_bf16 v[38:41], v[74:77], v[42:45], v[38:41]
	ds_read_b128 v[42:45], v154 offset:320
	s_waitcnt vmcnt(11) lgkmcnt(0)
	v_mfma_f32_16x16x32_bf16 v[38:41], v[78:81], v[42:45], v[38:41]
	ds_read_b128 v[42:45], v154 offset:384
	s_waitcnt vmcnt(10) lgkmcnt(0)
	v_mfma_f32_16x16x32_bf16 v[38:41], v[82:85], v[42:45], v[38:41]
	ds_read_b128 v[42:45], v154 offset:448
	s_waitcnt vmcnt(9) lgkmcnt(0)
	v_mfma_f32_16x16x32_bf16 v[38:41], v[86:89], v[42:45], v[38:41]
	s_nop 7
	ds_write_b128 v46, v[38:41]
	ds_read_b128 v[38:41], v154 offset:8448
	ds_read_b128 v[42:45], v154 offset:8512
	s_waitcnt lgkmcnt(1)
	v_mfma_f32_16x16x32_bf16 v[38:41], v[34:37], v[38:41], 0
	s_waitcnt lgkmcnt(0)
	v_mfma_f32_16x16x32_bf16 v[38:41], v[54:57], v[42:45], v[38:41]
	ds_read_b128 v[42:45], v154 offset:8576
	s_waitcnt lgkmcnt(0)
	v_mfma_f32_16x16x32_bf16 v[38:41], v[58:61], v[42:45], v[38:41]
	ds_read_b128 v[42:45], v154 offset:8640
	s_waitcnt lgkmcnt(0)
	v_mfma_f32_16x16x32_bf16 v[38:41], v[62:65], v[42:45], v[38:41]
	ds_read_b128 v[42:45], v154 offset:8704
	s_waitcnt lgkmcnt(0)
	v_mfma_f32_16x16x32_bf16 v[38:41], v[74:77], v[42:45], v[38:41]
	ds_read_b128 v[42:45], v154 offset:8768
	s_waitcnt lgkmcnt(0)
	v_mfma_f32_16x16x32_bf16 v[38:41], v[78:81], v[42:45], v[38:41]
	ds_read_b128 v[42:45], v154 offset:8832
	s_waitcnt lgkmcnt(0)
	v_mfma_f32_16x16x32_bf16 v[38:41], v[82:85], v[42:45], v[38:41]
	ds_read_b128 v[42:45], v154 offset:8896
	s_waitcnt lgkmcnt(0)
	v_mfma_f32_16x16x32_bf16 v[38:41], v[86:89], v[42:45], v[38:41]
	s_nop 7
	ds_write_b128 v46, v[38:41] offset:8448
	ds_read_b128 v[38:41], v154 offset:16896
	ds_read_b128 v[42:45], v154 offset:16960
	s_waitcnt lgkmcnt(1)
	v_mfma_f32_16x16x32_bf16 v[38:41], v[34:37], v[38:41], 0
	s_waitcnt lgkmcnt(0)
	v_mfma_f32_16x16x32_bf16 v[38:41], v[54:57], v[42:45], v[38:41]
	ds_read_b128 v[42:45], v154 offset:17024
	s_waitcnt lgkmcnt(0)
	v_mfma_f32_16x16x32_bf16 v[38:41], v[58:61], v[42:45], v[38:41]
	ds_read_b128 v[42:45], v154 offset:17088
	s_waitcnt lgkmcnt(0)
	v_mfma_f32_16x16x32_bf16 v[38:41], v[62:65], v[42:45], v[38:41]
	ds_read_b128 v[42:45], v154 offset:17152
	s_waitcnt lgkmcnt(0)
	v_mfma_f32_16x16x32_bf16 v[38:41], v[74:77], v[42:45], v[38:41]
	ds_read_b128 v[42:45], v154 offset:17216
	s_waitcnt lgkmcnt(0)
	v_mfma_f32_16x16x32_bf16 v[38:41], v[78:81], v[42:45], v[38:41]
	ds_read_b128 v[42:45], v154 offset:17280
	s_waitcnt lgkmcnt(0)
	v_mfma_f32_16x16x32_bf16 v[38:41], v[82:85], v[42:45], v[38:41]
	ds_read_b128 v[42:45], v154 offset:17344
	s_waitcnt lgkmcnt(0)
	v_mfma_f32_16x16x32_bf16 v[38:41], v[86:89], v[42:45], v[38:41]
	s_nop 7
	ds_write_b128 v46, v[38:41] offset:16896
	ds_read_b128 v[38:41], v154 offset:25344
	s_waitcnt lgkmcnt(0)
	v_mfma_f32_16x16x32_bf16 v[34:37], v[34:37], v[38:41], 0
	ds_read_b128 v[38:41], v154 offset:25408
	s_waitcnt lgkmcnt(0)
	v_mfma_f32_16x16x32_bf16 v[34:37], v[54:57], v[38:41], v[34:37]
	ds_read_b128 v[38:41], v154 offset:25472
	s_waitcnt lgkmcnt(0)
	v_mfma_f32_16x16x32_bf16 v[34:37], v[58:61], v[38:41], v[34:37]
	ds_read_b128 v[38:41], v154 offset:25536
	s_waitcnt lgkmcnt(0)
	v_mfma_f32_16x16x32_bf16 v[34:37], v[62:65], v[38:41], v[34:37]
	ds_read_b128 v[38:41], v154 offset:25600
	s_waitcnt lgkmcnt(0)
	v_mfma_f32_16x16x32_bf16 v[34:37], v[74:77], v[38:41], v[34:37]
	ds_read_b128 v[38:41], v154 offset:25664
	s_waitcnt lgkmcnt(0)
	v_mfma_f32_16x16x32_bf16 v[34:37], v[78:81], v[38:41], v[34:37]
	ds_read_b128 v[38:41], v154 offset:25728
	s_waitcnt lgkmcnt(0)
	v_mfma_f32_16x16x32_bf16 v[34:37], v[82:85], v[38:41], v[34:37]
	ds_read_b128 v[38:41], v154 offset:25792
	s_waitcnt lgkmcnt(0)
	v_mfma_f32_16x16x32_bf16 v[34:37], v[86:89], v[38:41], v[34:37]
	s_nop 7
	ds_write_b128 v46, v[34:37] offset:25344
	v_mov_b32_e32 v35, s15
	v_or_b32_e32 v34, s14, v186
	s_lshl_b64 s[14:15], s[6:7], 12
	v_lshl_add_u64 v[36:37], s[14:15], 0, v[34:35]
	v_lshlrev_b64 v[36:37], 2, v[36:37]
	s_waitcnt lgkmcnt(0)
	s_barrier
	v_lshl_add_u64 v[38:39], s[58:59], 0, v[36:37]
	global_load_dword v40, v[38:39], off
	v_lshl_add_u64 v[38:39], s[60:61], 0, v[36:37]
	global_load_dword v41, v[38:39], off
	s_waitcnt vmcnt(1)
	v_cvt_pk_bf16_f32 v38, v40, v115
	v_add_u32_e32 v39, s9, v146
	ds_write_b16 v39, v38
	s_waitcnt vmcnt(0)
	v_cvt_pk_bf16_f32 v38, v41, v115
	s_mul_i32 s9, s10, 0x1080
	ds_write_b16 v39, v38 offset:128
	v_add_u32_e32 v38, s9, v147
	ds_read2st64_b32 v[38:39], v38 offset1:1
	s_lshl_b32 s7, s10, 3
	s_or_b32 s7, s7, 1
	s_mul_i32 s9, s7, 0x110
	s_mulk_i32 s7, 0x210
	v_lshl_add_u64 v[36:37], s[68:69], 0, v[36:37]
	s_lshl_b64 s[14:15], s[28:29], 12
	s_waitcnt lgkmcnt(0)
	v_fmac_f32_e32 v39, v91, v40
	v_fma_f32 v38, -v91, v41, v38
	v_fmac_f32_e32 v38, v90, v40
	v_fmac_f32_e32 v39, v90, v41
	v_cvt_pk_bf16_f32 v40, v38, v115
	v_add_u32_e32 v41, s9, v146
	ds_write_b16 v41, v40
	v_cvt_pk_bf16_f32 v40, v39, v115
	ds_write_b16 v41, v40 offset:128
	v_add_u32_e32 v40, s7, v147
	ds_read2st64_b32 v[40:41], v40 offset1:1
	s_mul_i32 s9, s28, 0x220
	s_lshl_b32 s7, s28, 1
	s_or_b32 s7, s7, 1
	s_waitcnt lgkmcnt(0)
	v_fma_f32 v40, -v91, v39, v40
	v_fmac_f32_e32 v40, v90, v38
	v_fmac_f32_e32 v41, v91, v38
	v_add_co_u32_e32 v38, vcc, s41, v36
	v_fmac_f32_e32 v41, v90, v39
	s_nop 0
	v_addc_co_u32_e32 v39, vcc, 0, v37, vcc
	v_add_co_u32_e32 v36, vcc, s44, v36
	global_store_dword v[38:39], v40, off
	s_nop 0
	v_addc_co_u32_e32 v37, vcc, 0, v37, vcc
	global_store_dword v[36:37], v41, off
	v_lshl_add_u64 v[36:37], s[14:15], 0, v[34:35]
	v_lshlrev_b64 v[38:39], 2, v[36:37]
	v_lshl_add_u64 v[36:37], s[58:59], 0, v[38:39]
	global_load_dword v42, v[36:37], off
	v_lshl_add_u64 v[36:37], s[60:61], 0, v[38:39]
	global_load_dword v43, v[36:37], off
	s_waitcnt vmcnt(1)
	v_cvt_pk_bf16_f32 v37, v42, v115
	v_add_u32_e32 v36, s9, v146
	ds_write_b16 v36, v37
	s_waitcnt vmcnt(0)
	v_cvt_pk_bf16_f32 v37, v43, v115
	s_mul_i32 s9, s28, 0x420
	ds_write_b16 v36, v37 offset:128
	v_add_u32_e32 v37, s9, v147
	ds_read2st64_b32 v[40:41], v37 offset1:1
	s_mul_i32 s9, s7, 0x110
	s_mulk_i32 s7, 0x210
	v_lshl_add_u64 v[38:39], s[68:69], 0, v[38:39]
	s_or_b32 s28, s6, 2
	s_lshl_b64 s[14:15], s[28:29], 12
	s_or_b32 s6, s6, 3
	s_waitcnt lgkmcnt(0)
	v_fmac_f32_e32 v41, v91, v42
	v_fma_f32 v40, -v91, v43, v40
	v_fmac_f32_e32 v40, v90, v42
	v_fmac_f32_e32 v41, v90, v43
	v_cvt_pk_bf16_f32 v42, v40, v115
	v_add_u32_e32 v43, s9, v146
	ds_write_b16 v43, v42
	v_cvt_pk_bf16_f32 v42, v41, v115
	ds_write_b16 v43, v42 offset:128
	v_add_u32_e32 v42, s7, v147
	ds_read2st64_b32 v[42:43], v42 offset1:1
	s_lshl_b32 s7, s28, 1
	s_or_b32 s7, s7, 1
	s_mul_i32 s9, s7, 0x110
	s_mulk_i32 s7, 0x210
	s_waitcnt lgkmcnt(0)
	v_fma_f32 v42, -v91, v41, v42
	v_fmac_f32_e32 v42, v90, v40
	v_fmac_f32_e32 v43, v91, v40
	v_add_co_u32_e32 v40, vcc, s41, v38
	v_fmac_f32_e32 v43, v90, v41
	s_nop 0
	v_addc_co_u32_e32 v41, vcc, 0, v39, vcc
	v_add_co_u32_e32 v38, vcc, s44, v38
	global_store_dword v[40:41], v42, off
	s_nop 0
	v_addc_co_u32_e32 v39, vcc, 0, v39, vcc
	global_store_dword v[38:39], v43, off
	v_lshl_add_u64 v[38:39], s[14:15], 0, v[34:35]
	v_lshlrev_b64 v[38:39], 2, v[38:39]
	v_lshl_add_u64 v[40:41], s[58:59], 0, v[38:39]
	global_load_dword v42, v[40:41], off
	v_lshl_add_u64 v[40:41], s[60:61], 0, v[38:39]
	global_load_dword v43, v[40:41], off
	s_waitcnt vmcnt(1)
	v_cvt_pk_bf16_f32 v40, v42, v115
	ds_write_b16 v36, v40 offset:544
	s_waitcnt vmcnt(0)
	v_cvt_pk_bf16_f32 v40, v43, v115
	ds_write_b16 v36, v40 offset:672
	v_add_u32_e32 v40, 32, v37
	ds_read2st64_b32 v[40:41], v40 offset0:4 offset1:5
	v_lshl_add_u64 v[38:39], s[68:69], 0, v[38:39]
	s_waitcnt lgkmcnt(0)
	v_fmac_f32_e32 v41, v91, v42
	v_fma_f32 v40, -v91, v43, v40
	v_fmac_f32_e32 v40, v90, v42
	v_fmac_f32_e32 v41, v90, v43
	v_cvt_pk_bf16_f32 v42, v40, v115
	v_add_u32_e32 v43, s9, v146
	ds_write_b16 v43, v42
	v_cvt_pk_bf16_f32 v42, v41, v115
	ds_write_b16 v43, v42 offset:128
	v_add_u32_e32 v42, s7, v147
	ds_read2st64_b32 v[42:43], v42 offset1:1
	s_mov_b32 s7, s11
	s_lshl_b64 s[14:15], s[6:7], 12
	v_lshl_add_u64 v[34:35], s[14:15], 0, v[34:35]
	v_lshlrev_b64 v[34:35], 2, v[34:35]
	s_waitcnt lgkmcnt(0)
	v_fma_f32 v42, -v91, v41, v42
	v_fmac_f32_e32 v42, v90, v40
	v_fmac_f32_e32 v43, v91, v40
	v_add_co_u32_e32 v40, vcc, s41, v38
	v_fmac_f32_e32 v43, v90, v41
	s_nop 0
	v_addc_co_u32_e32 v41, vcc, 0, v39, vcc
	v_add_co_u32_e32 v38, vcc, s44, v38
	global_store_dword v[40:41], v42, off
	s_nop 0
	v_addc_co_u32_e32 v39, vcc, 0, v39, vcc
	global_store_dword v[38:39], v43, off
	v_lshl_add_u64 v[38:39], s[58:59], 0, v[34:35]
	global_load_dword v40, v[38:39], off
	v_lshl_add_u64 v[38:39], s[60:61], 0, v[34:35]
	global_load_dword v38, v[38:39], off
	s_waitcnt vmcnt(1)
	v_cvt_pk_bf16_f32 v39, v40, v115
	ds_write_b16 v36, v39 offset:1088
	s_waitcnt vmcnt(0)
	v_cvt_pk_bf16_f32 v39, v38, v115
	ds_write_b16 v36, v39 offset:1216
	v_add_u32_e32 v36, 64, v37
	ds_read2st64_b32 v[36:37], v36 offset0:8 offset1:9
	s_lshl_b32 s6, s6, 1
	s_or_b32 s6, s6, 1
	s_mul_i32 s7, s6, 0x110
	v_add_u32_e32 v39, s7, v146
	s_mulk_i32 s6, 0x210
	v_lshl_add_u64 v[34:35], s[68:69], 0, v[34:35]
	s_waitcnt lgkmcnt(0)
	v_fmac_f32_e32 v37, v91, v40
	v_fma_f32 v36, -v91, v38, v36
	v_fmac_f32_e32 v36, v90, v40
	v_fmac_f32_e32 v37, v90, v38
	v_cvt_pk_bf16_f32 v38, v36, v115
	ds_write_b16 v39, v38
	v_cvt_pk_bf16_f32 v38, v37, v115
	ds_write_b16 v39, v38 offset:128
	v_add_u32_e32 v38, s6, v147
	ds_read2st64_b32 v[38:39], v38 offset1:1
	s_lshr_b32 s6, s46, 7
	s_waitcnt lgkmcnt(0)
	v_fma_f32 v38, -v91, v37, v38
	v_fmac_f32_e32 v38, v90, v36
	v_fmac_f32_e32 v39, v91, v36
	v_add_co_u32_e32 v36, vcc, s41, v34
	v_fmac_f32_e32 v39, v90, v37
	s_nop 0
	v_addc_co_u32_e32 v37, vcc, 0, v35, vcc
	v_add_co_u32_e32 v34, vcc, s44, v34
	global_store_dword v[36:37], v38, off
	s_nop 0
	v_addc_co_u32_e32 v35, vcc, 0, v35, vcc
	global_store_dword v[34:35], v39, off
	s_waitcnt lgkmcnt(0)
	s_barrier
	ds_read_b128 v[46:49], v152
	ds_read_b128 v[74:77], v152 offset:128
	ds_read_b128 v[42:45], v152 offset:4352
	ds_read_b128 v[38:41], v152 offset:8704
	ds_read_b128 v[34:37], v152 offset:13056
	s_waitcnt lgkmcnt(4)
	v_mfma_f32_16x16x32_bf16 v[50:53], v[30:33], v[46:49], 0
	ds_read_b128 v[70:73], v152 offset:4480
	ds_read_b128 v[90:93], v152 offset:8896
	s_waitcnt lgkmcnt(4)
	v_mfma_f32_16x16x32_bf16 v[54:57], v[30:33], v[42:45], 0
	s_waitcnt lgkmcnt(3)
	v_mfma_f32_16x16x32_bf16 v[58:61], v[30:33], v[38:41], 0
	s_waitcnt lgkmcnt(2)
	v_mfma_f32_16x16x32_bf16 v[62:65], v[30:33], v[34:37], 0
	ds_read_b128 v[30:33], v152 offset:64
	s_waitcnt lgkmcnt(0)
	v_mfma_f32_16x16x32_bf16 v[66:69], v[22:25], v[30:33], v[50:53]
	s_nop 2
	ds_read_b128 v[50:53], v152 offset:4416
	v_mfma_f32_16x16x32_bf16 v[86:89], v[26:29], v[74:77], v[66:69]
	s_nop 2
	ds_read_b128 v[66:69], v152 offset:8832
	s_waitcnt lgkmcnt(1)
	v_mfma_f32_16x16x32_bf16 v[78:81], v[22:25], v[50:53], v[54:57]
	s_nop 2
	ds_read_b128 v[54:57], v152 offset:8768
	s_waitcnt lgkmcnt(0)
	v_mfma_f32_16x16x32_bf16 v[82:85], v[22:25], v[54:57], v[58:61]
	s_nop 2
	ds_read_b128 v[58:61], v152 offset:13120
	s_waitcnt lgkmcnt(0)
	v_mfma_f32_16x16x32_bf16 v[22:25], v[22:25], v[58:61], v[62:65]
	s_nop 2
	ds_read_b128 v[62:65], v152 offset:13184
	v_mfma_f32_16x16x32_bf16 v[94:97], v[26:29], v[66:69], v[82:85]
	s_nop 2
	ds_read_b128 v[82:85], v152 offset:192
	v_mfma_f32_16x16x32_bf16 v[78:81], v[26:29], v[70:73], v[78:81]
	s_waitcnt lgkmcnt(1)
	v_mfma_f32_16x16x32_bf16 v[98:101], v[26:29], v[62:65], v[22:25]
	s_waitcnt lgkmcnt(0)
	v_mfma_f32_16x16x32_bf16 v[26:29], v[18:21], v[82:85], v[86:89]
	s_nop 2
	ds_read_b128 v[86:89], v152 offset:4544
	v_mfma_f32_16x16x32_bf16 v[22:25], v[18:21], v[90:93], v[94:97]
	s_nop 2
	ds_read_b128 v[94:97], v152 offset:13248
	s_waitcnt lgkmcnt(1)
	v_mfma_f32_16x16x32_bf16 v[78:81], v[18:21], v[86:89], v[78:81]
	s_waitcnt lgkmcnt(0)
	v_mfma_f32_16x16x32_bf16 v[18:21], v[18:21], v[94:97], v[98:101]
	ds_read_b128 v[110:113], v154
	ds_read_b128 v[106:109], v154 offset:8448
	ds_read_b128 v[102:105], v154 offset:16896
	ds_read_b128 v[98:101], v154 offset:25344
	ds_read_b128 v[156:159], v155
